# grid barrier: member workgroups spin on the top-level generation word (one hop fewer after the last XCD leader arrives)
# speedup vs baseline: 1.0088x; 1.0009x over previous
.LBB0_111:
	s_or_b64 exec, exec, s[8:9]
	v_cvt_f32_u32_e32 v4, v2
	s_waitcnt vmcnt(0)
	v_readfirstlane_b32 s6, v3
	v_sub_u32_e32 v3, 0, v2
	v_rcp_iflag_f32_e32 v4, v4
	v_add_u32_e32 v5, s6, v1
	v_mul_f32_e32 v4, 0x4f7ffffe, v4
	v_cvt_u32_f32_e32 v4, v4
	v_mul_lo_u32 v1, v3, v4
	v_mul_hi_u32 v1, v4, v1
	v_add_u32_e32 v1, v4, v1
	v_mul_hi_u32 v1, v5, v1
	v_mul_lo_u32 v3, v1, v2
	v_sub_u32_e32 v3, v5, v3
	v_add_u32_e32 v4, 1, v1
	v_cmp_ge_u32_e32 vcc, v3, v2
	s_nop 1
	v_cndmask_b32_e32 v1, v1, v4, vcc
	v_sub_u32_e32 v4, v3, v2
	v_cndmask_b32_e32 v3, v3, v4, vcc
	v_add_u32_e32 v4, 1, v1
	v_cmp_ge_u32_e32 vcc, v3, v2
	v_add_u32_e32 v3, 1, v5
	s_nop 0
	v_cndmask_b32_e32 v1, v1, v4, vcc
	v_mul_lo_u32 v4, v2, v1
	v_add_u32_e32 v2, v4, v2
	v_cmp_ne_u32_e32 vcc, v3, v2
	s_and_saveexec_b64 s[6:7], vcc
	s_xor_b64 s[6:7], exec, s[6:7]
	s_cbranch_execz .LBB0_125
	s_waitcnt lgkmcnt(0)
	v_mov_b32_e32 v0, 0x3100
	global_load_dword v0, v0, s[50:51] offset:1024 sc1
	s_add_u32 s10, s50, 0x3500
	s_addc_u32 s11, s51, 0
	s_waitcnt vmcnt(0)
	v_cmp_eq_u32_e32 vcc, v0, v1
	s_and_saveexec_b64 s[8:9], vcc
	s_cbranch_execz .LBB0_124
	s_mov_b32 s22, 1
	s_mov_b64 s[12:13], 0
	v_mov_b32_e32 v0, 0
	s_branch .LBB0_115

.LBB0_300:
	s_or_b64 exec, exec, s[14:15]
	v_cvt_f32_u32_e32 v4, v2
	s_waitcnt vmcnt(0)
	v_readfirstlane_b32 s12, v3
	v_sub_u32_e32 v3, 0, v2
	v_rcp_iflag_f32_e32 v4, v4
	v_add_u32_e32 v5, s12, v1
	v_mul_f32_e32 v4, 0x4f7ffffe, v4
	v_cvt_u32_f32_e32 v4, v4
	v_mul_lo_u32 v1, v3, v4
	v_mul_hi_u32 v1, v4, v1
	v_add_u32_e32 v1, v4, v1
	v_mul_hi_u32 v1, v5, v1
	v_mul_lo_u32 v3, v1, v2
	v_sub_u32_e32 v3, v5, v3
	v_add_u32_e32 v4, 1, v1
	v_cmp_ge_u32_e32 vcc, v3, v2
	s_nop 1
	v_cndmask_b32_e32 v1, v1, v4, vcc
	v_sub_u32_e32 v4, v3, v2
	v_cndmask_b32_e32 v3, v3, v4, vcc
	v_add_u32_e32 v4, 1, v1
	v_cmp_ge_u32_e32 vcc, v3, v2
	v_add_u32_e32 v3, 1, v5
	s_nop 0
	v_cndmask_b32_e32 v1, v1, v4, vcc
	v_mul_lo_u32 v4, v2, v1
	v_add_u32_e32 v2, v4, v2
	v_cmp_ne_u32_e32 vcc, v3, v2
	s_and_saveexec_b64 s[12:13], vcc
	s_xor_b64 s[12:13], exec, s[12:13]
	s_cbranch_execz .LBB0_314
	s_waitcnt lgkmcnt(0)
	v_mov_b32_e32 v0, 0x3100
	global_load_dword v0, v0, s[50:51] offset:1024 sc1
	s_add_u32 s16, s50, 0x3500
	s_addc_u32 s17, s51, 0
	s_waitcnt vmcnt(0)
	v_cmp_eq_u32_e32 vcc, v0, v1
	s_and_saveexec_b64 s[14:15], vcc
	s_cbranch_execz .LBB0_313
	s_mov_b32 s28, 1
	s_mov_b64 s[18:19], 0
	v_mov_b32_e32 v0, 0
	s_branch .LBB0_304

.LBB0_536:
	s_or_b64 exec, exec, s[12:13]
	v_cvt_f32_u32_e32 v4, v2
	s_waitcnt vmcnt(0)
	v_readfirstlane_b32 s6, v3
	v_sub_u32_e32 v3, 0, v2
	v_rcp_iflag_f32_e32 v4, v4
	v_add_u32_e32 v5, s6, v1
	v_mul_f32_e32 v4, 0x4f7ffffe, v4
	v_cvt_u32_f32_e32 v4, v4
	v_mul_lo_u32 v1, v3, v4
	v_mul_hi_u32 v1, v4, v1
	v_add_u32_e32 v1, v4, v1
	v_mul_hi_u32 v1, v5, v1
	v_mul_lo_u32 v3, v1, v2
	v_sub_u32_e32 v3, v5, v3
	v_add_u32_e32 v4, 1, v1
	v_cmp_ge_u32_e32 vcc, v3, v2
	s_nop 1
	v_cndmask_b32_e32 v1, v1, v4, vcc
	v_sub_u32_e32 v4, v3, v2
	v_cndmask_b32_e32 v3, v3, v4, vcc
	v_add_u32_e32 v4, 1, v1
	v_cmp_ge_u32_e32 vcc, v3, v2
	v_add_u32_e32 v3, 1, v5
	s_nop 0
	v_cndmask_b32_e32 v1, v1, v4, vcc
	v_mul_lo_u32 v4, v2, v1
	v_add_u32_e32 v2, v4, v2
	v_cmp_ne_u32_e32 vcc, v3, v2
	s_and_saveexec_b64 s[6:7], vcc
	s_xor_b64 s[6:7], exec, s[6:7]
	s_cbranch_execz .LBB0_550
	s_waitcnt lgkmcnt(0)
	v_mov_b32_e32 v0, 0x3100
	global_load_dword v0, v0, s[50:51] offset:1024 sc1
	s_add_u32 s14, s50, 0x3500
	s_addc_u32 s15, s51, 0
	s_waitcnt vmcnt(0)
	v_cmp_eq_u32_e32 vcc, v0, v1
	s_and_saveexec_b64 s[12:13], vcc
	s_cbranch_execz .LBB0_549
	s_mov_b32 s26, 1
	s_mov_b64 s[16:17], 0
	v_mov_b32_e32 v0, 0
	s_branch .LBB0_540

.LBB0_746:
	s_or_b64 exec, exec, s[14:15]
	v_cvt_f32_u32_e32 v4, v2
	s_waitcnt vmcnt(0)
	v_readfirstlane_b32 s6, v3
	v_sub_u32_e32 v3, 0, v2
	v_rcp_iflag_f32_e32 v4, v4
	v_add_u32_e32 v5, s6, v1
	v_mul_f32_e32 v4, 0x4f7ffffe, v4
	v_cvt_u32_f32_e32 v4, v4
	v_mul_lo_u32 v1, v3, v4
	v_mul_hi_u32 v1, v4, v1
	v_add_u32_e32 v1, v4, v1
	v_mul_hi_u32 v1, v5, v1
	v_mul_lo_u32 v3, v1, v2
	v_sub_u32_e32 v3, v5, v3
	v_add_u32_e32 v4, 1, v1
	v_cmp_ge_u32_e32 vcc, v3, v2
	s_nop 1
	v_cndmask_b32_e32 v1, v1, v4, vcc
	v_sub_u32_e32 v4, v3, v2
	v_cndmask_b32_e32 v3, v3, v4, vcc
	v_add_u32_e32 v4, 1, v1
	v_cmp_ge_u32_e32 vcc, v3, v2
	v_add_u32_e32 v3, 1, v5
	s_nop 0
	v_cndmask_b32_e32 v1, v1, v4, vcc
	v_mul_lo_u32 v4, v2, v1
	v_add_u32_e32 v2, v4, v2
	v_cmp_ne_u32_e32 vcc, v3, v2
	s_and_saveexec_b64 s[6:7], vcc
	s_xor_b64 s[6:7], exec, s[6:7]
	s_cbranch_execz .LBB0_760
	s_waitcnt lgkmcnt(0)
	v_mov_b32_e32 v0, 0x3100
	global_load_dword v0, v0, s[50:51] offset:1024 sc1
	s_add_u32 s16, s50, 0x3500
	s_addc_u32 s17, s51, 0
	s_waitcnt vmcnt(0)
	v_cmp_eq_u32_e32 vcc, v0, v1
	s_and_saveexec_b64 s[14:15], vcc
	s_cbranch_execz .LBB0_759
	s_mov_b32 s28, 1
	s_mov_b64 s[18:19], 0
	v_mov_b32_e32 v0, 0
	s_branch .LBB0_750

.LBB0_1017:
	s_or_b64 exec, exec, s[10:11]
	v_cvt_f32_u32_e32 v4, v2
	s_waitcnt vmcnt(0)
	v_readfirstlane_b32 s6, v3
	v_sub_u32_e32 v3, 0, v2
	v_rcp_iflag_f32_e32 v4, v4
	v_add_u32_e32 v5, s6, v1
	v_mul_f32_e32 v4, 0x4f7ffffe, v4
	v_cvt_u32_f32_e32 v4, v4
	v_mul_lo_u32 v1, v3, v4
	v_mul_hi_u32 v1, v4, v1
	v_add_u32_e32 v1, v4, v1
	v_mul_hi_u32 v1, v5, v1
	v_mul_lo_u32 v3, v1, v2
	v_sub_u32_e32 v3, v5, v3
	v_add_u32_e32 v4, 1, v1
	v_cmp_ge_u32_e32 vcc, v3, v2
	s_nop 1
	v_cndmask_b32_e32 v1, v1, v4, vcc
	v_sub_u32_e32 v4, v3, v2
	v_cndmask_b32_e32 v3, v3, v4, vcc
	v_add_u32_e32 v4, 1, v1
	v_cmp_ge_u32_e32 vcc, v3, v2
	v_add_u32_e32 v3, 1, v5
	s_nop 0
	v_cndmask_b32_e32 v1, v1, v4, vcc
	v_mul_lo_u32 v4, v2, v1
	v_add_u32_e32 v2, v4, v2
	v_cmp_ne_u32_e32 vcc, v3, v2
	s_and_saveexec_b64 s[6:7], vcc
	s_xor_b64 s[6:7], exec, s[6:7]
	s_cbranch_execz .LBB0_1031
	s_waitcnt lgkmcnt(0)
	v_mov_b32_e32 v0, 0x3100
	global_load_dword v0, v0, s[50:51] offset:1024 sc1
	s_add_u32 s12, s50, 0x3500
	s_addc_u32 s13, s51, 0
	s_waitcnt vmcnt(0)
	v_cmp_eq_u32_e32 vcc, v0, v1
	s_and_saveexec_b64 s[10:11], vcc
	s_cbranch_execz .LBB0_1030
	s_mov_b32 s24, 1
	s_mov_b64 s[14:15], 0
	v_mov_b32_e32 v0, 0
	s_branch .LBB0_1021
